# first grid barrier: the 16 per-XCC census counter loads issued together with one wait instead of one round trip each
# speedup vs baseline: 1.0154x; 1.0073x over previous
.LBB0_595:
	global_load_dword v3, v97, s[64:65] sc1
	s_waitcnt lgkmcnt(0)
	global_load_dword v0, v97, s[68:69] sc1
	global_load_dword v1, v97, s[70:71] sc1
	global_load_dword v2, v97, s[36:37] sc1
	s_mov_b64 s[10:11], -1
	v_readlane_b32 s8, v249, 44
	v_readlane_b32 s9, v249, 45
	s_nop 4
	global_load_dword v4, v97, s[8:9] sc1
	v_readlane_b32 s8, v249, 46
	v_readlane_b32 s9, v249, 47
	s_nop 4
	global_load_dword v5, v97, s[8:9] sc1
	v_readlane_b32 s8, v249, 48
	v_readlane_b32 s9, v249, 49
	s_nop 4
	global_load_dword v6, v97, s[8:9] sc1
	v_readlane_b32 s8, v249, 50
	v_readlane_b32 s9, v249, 51
	s_nop 4
	global_load_dword v7, v97, s[8:9] sc1
	v_readlane_b32 s8, v249, 52
	v_readlane_b32 s9, v249, 53
	s_nop 4
	global_load_dword v8, v97, s[8:9] sc1
	v_readlane_b32 s8, v249, 54
	v_readlane_b32 s9, v249, 55
	s_nop 4
	global_load_dword v9, v97, s[8:9] sc1
	v_readlane_b32 s8, v249, 56
	v_readlane_b32 s9, v249, 57
	s_nop 4
	global_load_dword v10, v97, s[8:9] sc1
	v_readlane_b32 s8, v249, 58
	v_readlane_b32 s9, v249, 59
	s_nop 4
	global_load_dword v11, v97, s[8:9] sc1
	v_readlane_b32 s8, v249, 60
	v_readlane_b32 s9, v249, 61
	s_nop 4
	global_load_dword v12, v97, s[8:9] sc1
	v_readlane_b32 s8, v249, 62
	v_readlane_b32 s9, v249, 63
	s_nop 4
	global_load_dword v13, v97, s[8:9] sc1
	v_readlane_b32 s8, v247, 0
	v_readlane_b32 s9, v247, 1
	s_nop 4
	global_load_dword v14, v97, s[8:9] sc1
	v_readlane_b32 s8, v247, 2
	v_readlane_b32 s9, v247, 3
	s_nop 4
	global_load_dword v15, v97, s[8:9] sc1
	s_mov_b64 s[8:9], -1
	s_waitcnt vmcnt(0)
	v_add_u32_e32 v16, v0, v3
	v_add_u32_e32 v16, v16, v1
	v_add_u32_e32 v16, v16, v2
	v_add_u32_e32 v16, v16, v4
	v_add_u32_e32 v16, v16, v5
	v_add_u32_e32 v16, v16, v6
	v_add_u32_e32 v16, v16, v7
	v_add_u32_e32 v16, v16, v8
	v_add_u32_e32 v16, v16, v9
	v_add_u32_e32 v16, v16, v10
	v_add_u32_e32 v16, v16, v11
	v_add_u32_e32 v16, v16, v12
	v_add_u32_e32 v16, v16, v13
	v_add_u32_e32 v16, v16, v14
	v_add_u32_e32 v16, v16, v15
	v_cmp_eq_u32_e32 vcc, s19, v16
	s_cbranch_vccnz .LBB0_594
	s_and_b32 s4, s3, 0xff
	s_cmp_eq_u32 s4, 0
	s_mov_b64 s[12:13], -1
	s_sleep 1
	s_cbranch_scc1 .LBB0_599
	s_and_b64 vcc, exec, s[12:13]
	s_cbranch_vccz .LBB0_594
